# fast loops also take the last full tile pair before the diagonal; 16-instruction max tree (two chains of seven v_max3 + the two remaining scores)
# baseline (speedup 1.0000x reference)
; #define ATT_BAR() do { asm volatile("s_waitcnt lgkmcnt(0)" ::: "memory"); __builtin_amdgcn_s_barrier(); asm volatile("" ::: "memory"); } while (0)
; template <int DK, int DV>
; __device__ __forceinline__ void attn_unit(LAS unsigned char* lds, const bf16* Qp, int ldq, const bf16* Kp, int ldk, const bf16* VTp, bf16* Op, int ldo, int qb) {
;     ...
;     ATT_LOAD(0, kra, vra); ATT_LOAD(1, krb, vrb);
;     ATT_STORE(0, kra, vra); ATT_STORE(BUF, krb, vrb);
;     ATT_LOAD(2, krb, vrb);
;     __syncthreads();
;     float mrun = 0.f, lrun = 0.f;
;     f32x16 o[NDB];
; #pragma unroll
;     for (int db = 0; db < NDB; ++db)
; #pragma unroll
;         for (int r = 0; r < 16; ++r) o[db][r] = 0.f;
;     f32x16 s0, s1;
;     const f32x16 zacc = {0.f, 0.f, 0.f, 0.f, 0.f, 0.f, 0.f, 0.f, 0.f, 0.f, 0.f, 0.f, 0.f, 0.f, 0.f, 0.f};
;     f32x16 negm = zacc;
;     constexpr float ATT_THR = 8.f;
;     ATT_QK(0, zacc);
;     if (grpB) ATT_BAR();
;     int bcur = 0, bnext = BUF, bfree = 2 * BUF;
; #pragma unroll 1
;     for (int t = 0; t < NT; t += 2) {
.LBB0_1036:
	ds_read_b128 v[196:199], v141
	ds_read_b128 v[200:203], v141 offset:1024
	ds_read_b128 v[204:207], v141 offset:2048
	ds_read_b128 v[208:211], v141 offset:3072
	ds_read_b128 v[212:215], v141 offset:4096
	ds_read_b128 v[216:219], v141 offset:5120
	v_or_b32_e32 v159, s46, v6
	v_mul_u32_u24_e32 v6, 0x90, v6
	v_lshlrev_b32_e32 v158, 2, v7
	v_lshl_add_u64 v[144:145], v[2:3], 1, s[4:5]
	v_lshl_add_u64 v[146:147], v[4:5], 1, s[4:5]
	v_mad_i64_i32 v[186:187], vcc, v150, s3, v[144:145]
	v_mad_i64_i32 v[188:189], vcc, v151, s3, v[146:147]
	v_add3_u32 v160, 0, v6, v0
	v_mov_b32_e32 v2, v1
	v_mov_b32_e32 v3, v1
	v_mov_b32_e32 v4, v1
	v_mov_b32_e32 v5, v1
	v_mov_b32_e32 v6, v1
	v_mov_b32_e32 v7, v1
	v_mov_b32_e32 v8, v1
	v_mov_b32_e32 v9, v1
	v_mov_b32_e32 v10, v1
	v_mov_b32_e32 v11, v1
	v_mov_b32_e32 v12, v1
	v_mov_b32_e32 v13, v1
	v_mov_b32_e32 v14, v1
	v_mov_b32_e32 v15, v1
	v_mov_b32_e32 v16, v1
	v_mov_b32_e32 v17, v1
	v_mov_b32_e32 v18, v1
	v_mov_b32_e32 v19, v1
	v_mov_b32_e32 v20, v1
	v_mov_b32_e32 v21, v1
	v_mov_b32_e32 v22, v1
	v_mov_b32_e32 v23, v1
	v_mov_b32_e32 v24, v1
	v_mov_b32_e32 v25, v1
	v_mov_b32_e32 v26, v1
	v_mov_b32_e32 v27, v1
	v_mov_b32_e32 v28, v1
	v_mov_b32_e32 v29, v1
	v_mov_b32_e32 v30, v1
	v_mov_b32_e32 v31, v1
	s_lshl_b32 s48, s0, 2
	v_mov_b32_e32 v0, v1
	v_mov_b64_e32 v[32:33], v[30:31]
	s_lshl_b32 s47, s1, 13
	v_ashrrev_i32_e32 v139, 31, v138
	s_add_i32 s49, s48, 4
	s_or_b32 s50, s48, 3
	s_or_b32 s51, s46, 31
	s_mov_b32 s54, 0
	s_sub_i32 s55, 0, s48
	s_sub_i32 s56, 0, s8
	v_subrev_u32_e32 v161, s8, v158
	v_mov_b32_e32 v66, v1
	v_mov_b32_e32 v67, v1
	v_mov_b32_e32 v68, v1
	v_mov_b32_e32 v69, v1
	v_mov_b32_e32 v70, v1
	v_mov_b32_e32 v71, v1
	v_mov_b32_e32 v72, v1
	v_mov_b32_e32 v73, v1
	v_mov_b32_e32 v74, v1
	v_mov_b32_e32 v75, v1
	v_mov_b32_e32 v76, v1
	v_mov_b32_e32 v77, v1
	v_mov_b32_e32 v78, v1
	v_mov_b32_e32 v79, v1
	v_mov_b32_e32 v80, v1
	v_mov_b32_e32 v81, v1
	s_mov_b32 s57, 0xb000
	s_movk_i32 s58, 0x5800
	v_mov_b32_e32 v162, 0
	v_mov_b32_e32 v163, 0
	s_mov_b32 s0, 0
	s_mov_b32 s59, 0
	v_mov_b64_e32 v[30:31], v[28:29]
	v_mov_b64_e32 v[28:29], v[26:27]
	v_mov_b64_e32 v[26:27], v[24:25]
	v_mov_b64_e32 v[24:25], v[22:23]
	v_mov_b64_e32 v[22:23], v[20:21]
	v_mov_b64_e32 v[20:21], v[18:19]
	v_mov_b64_e32 v[18:19], v[16:17]
	v_mov_b64_e32 v[16:17], v[14:15]
	v_mov_b64_e32 v[14:15], v[12:13]
	v_mov_b64_e32 v[12:13], v[10:11]
	v_mov_b64_e32 v[10:11], v[8:9]
	v_mov_b64_e32 v[8:9], v[6:7]
	v_mov_b64_e32 v[6:7], v[4:5]
	v_mov_b64_e32 v[4:5], v[2:3]
	v_mov_b64_e32 v[2:3], v[0:1]
	s_add_i32 s1, s59, 3
	s_cmp_lt_u32 s1, s49
	s_cselect_b32 s1, s1, s50
	s_lshl_b32 s8, s1, 6
	s_mul_i32 s4, s8, 0x600
	s_mov_b32 s5, 0
	v_lshl_add_u64 v[94:95], s[4:5], 0, v[186:187]
	v_lshl_add_u64 v[96:97], s[4:5], 0, v[188:189]
	v_lshl_add_u64 v[102:103], s[8:9], 1, v[142:143]
	global_load_dwordx4 v[98:101], v[94:95], off
	s_nop 0
	global_load_dwordx4 v[94:97], v[96:97], off
	global_load_dwordx4 v[102:105], v[102:103], off
	s_add_i32 s4, s55, s59
	s_cmp_lt_i32 s4, -1
	s_cbranch_scc1 .Lfm_entry

.Lfm_head:
	v_max3_f32 v0, v34, v35, v36
	v_max3_f32 v122, v50, v51, v52
	v_max3_f32 v0, v0, v37, v38
	v_max3_f32 v122, v122, v53, v54
	v_max3_f32 v0, v0, v39, v40
	v_max3_f32 v122, v122, v55, v56
	v_max3_f32 v0, v0, v41, v42
	v_max3_f32 v122, v122, v57, v58
	v_max3_f32 v0, v0, v43, v44
	v_max3_f32 v122, v122, v59, v60
	v_max3_f32 v0, v0, v45, v46
	v_max3_f32 v122, v122, v61, v62
	v_max3_f32 v0, v0, v47, v48
	v_max3_f32 v122, v122, v63, v64
	v_max3_f32 v0, v0, v122, v49
	v_max_f32_e32 v0, v0, v65
	s_cmp_lg_u32 s54, 0
	s_cselect_b64 s[20:21], -1, 0
	s_cmp_eq_u32 s54, 0
	s_cbranch_scc1 .Lfm_a_xchg
	v_cmp_lt_f32_e32 vcc, s35, v0
	s_cbranch_vccnz .Lfm_a_xchg
.Lfm_a_exp:
	v_exp_f32_e32 v34, v34
	v_exp_f32_e32 v50, v50
	v_exp_f32_e32 v35, v35
	v_exp_f32_e32 v51, v51
	v_exp_f32_e32 v42, v42
	v_exp_f32_e32 v58, v58
	v_exp_f32_e32 v43, v43
	v_exp_f32_e32 v59, v59
	v_exp_f32_e32 v36, v36
	v_exp_f32_e32 v52, v52
	v_exp_f32_e32 v37, v37
	v_exp_f32_e32 v53, v53
	v_exp_f32_e32 v44, v44
	v_exp_f32_e32 v60, v60
	v_exp_f32_e32 v45, v45
	v_exp_f32_e32 v61, v61
	v_exp_f32_e32 v38, v38
	v_exp_f32_e32 v54, v54
	v_exp_f32_e32 v39, v39
	v_exp_f32_e32 v55, v55
	v_exp_f32_e32 v46, v46
	v_exp_f32_e32 v62, v62
	v_exp_f32_e32 v47, v47
	v_exp_f32_e32 v63, v63
	v_exp_f32_e32 v40, v40
	v_exp_f32_e32 v56, v56
	v_exp_f32_e32 v41, v41
	v_exp_f32_e32 v57, v57
	v_exp_f32_e32 v48, v48
	v_exp_f32_e32 v64, v64
	v_exp_f32_e32 v49, v49
	v_exp_f32_e32 v65, v65
	v_pk_add_f32 v[122:123], v[34:35], v[50:51]
	v_pk_add_f32 v[124:125], v[36:37], v[52:53]
	v_pk_add_f32 v[126:127], v[38:39], v[54:55]
	v_pk_add_f32 v[128:129], v[40:41], v[56:57]
	v_pk_add_f32 v[130:131], v[42:43], v[58:59]
	v_pk_add_f32 v[132:133], v[44:45], v[60:61]
	v_pk_add_f32 v[134:135], v[46:47], v[62:63]
	v_pk_add_f32 v[136:137], v[48:49], v[64:65]
	v_pk_add_f32 v[122:123], v[122:123], v[124:125]
	v_pk_add_f32 v[126:127], v[126:127], v[128:129]
	v_pk_add_f32 v[130:131], v[130:131], v[132:133]
	v_pk_add_f32 v[134:135], v[134:135], v[136:137]
	v_pk_add_f32 v[122:123], v[122:123], v[126:127]
	v_pk_add_f32 v[130:131], v[130:131], v[134:135]
	v_pk_add_f32 v[122:123], v[122:123], v[130:131]
	v_add_f32_e32 v0, v122, v123
	v_cvt_pk_bf16_f32 v122, v34, v35
	v_cvt_pk_bf16_f32 v123, v36, v37
	v_cvt_pk_bf16_f32 v124, v38, v39
	v_cvt_pk_bf16_f32 v125, v40, v41
	v_cvt_pk_bf16_f32 v126, v42, v43
	v_cvt_pk_bf16_f32 v127, v44, v45
	v_cvt_pk_bf16_f32 v128, v46, v47
	v_cvt_pk_bf16_f32 v129, v48, v49
	v_cvt_pk_bf16_f32 v130, v50, v51
	v_cvt_pk_bf16_f32 v131, v52, v53
	v_cvt_pk_bf16_f32 v132, v54, v55
	v_cvt_pk_bf16_f32 v133, v56, v57
	v_cvt_pk_bf16_f32 v134, v58, v59
	v_cvt_pk_bf16_f32 v135, v60, v61
	v_cvt_pk_bf16_f32 v136, v62, v63
	v_cvt_pk_bf16_f32 v137, v64, v65
	v_add_f32_e32 v162, v162, v0
	s_waitcnt lgkmcnt(0)
	s_barrier
	v_mfma_f32_32x32x16_bf16 v[2:17], v[164:167], v[122:125], v[2:17]
	s_setprio 1
	v_add3_u32 v0, s57, v152, v153
	s_waitcnt vmcnt(3)
	ds_write_b128 v0, v[86:89]
	v_mfma_f32_32x32x16_bf16 v[18:33], v[168:171], v[122:125], v[18:33]
	v_add3_u32 v0, s57, v154, v155
	ds_write_b128 v0, v[90:93]
	v_mfma_f32_32x32x16_bf16 v[2:17], v[172:175], v[126:129], v[2:17]
	v_add3_u32 v0, s57, v156, v140
	ds_write_b128 v0, v[82:85] offset:13312
	v_add_u32_e32 v249, s60, v157
	v_mfma_f32_32x32x16_bf16 v[18:33], v[176:179], v[126:129], v[18:33]
	ds_read_b128 v[236:239], v249
	ds_read_b128 v[240:243], v249 offset:6656
	ds_read_b128 v[244:247], v249 offset:32
	v_mfma_f32_32x32x16_bf16 v[2:17], v[180:183], v[130:133], v[2:17]
	ds_read_b128 v[164:167], v249 offset:6688
	ds_read_b128 v[168:171], v249 offset:64
	ds_read_b128 v[172:175], v249 offset:6720
	v_mfma_f32_32x32x16_bf16 v[18:33], v[220:223], v[130:133], v[18:33]
	ds_read_b128 v[176:179], v249 offset:96
	ds_read_b128 v[180:183], v249 offset:6752
	ds_read_b128 v[220:223], v249 offset:128
	v_mfma_f32_32x32x16_bf16 v[2:17], v[224:227], v[134:137], v[2:17]
	ds_read_b128 v[224:227], v249 offset:6784
	v_mfma_f32_32x32x16_bf16 v[18:33], v[232:235], v[134:137], v[18:33]
	ds_read_b128 v[232:235], v249 offset:160
	s_waitcnt lgkmcnt(9)
	v_mfma_f32_32x32x16_bf16 v[34:49], v[236:239], v[196:199], v[66:81]
	ds_read_b128 v[236:239], v249 offset:6816
	s_add_i32 s0, s59, 4
	s_lshl_b32 s8, s0, 6
	v_mfma_f32_32x32x16_bf16 v[50:65], v[240:243], v[196:199], v[66:81]
	s_mul_i32 s0, s8, 0x600
	s_mov_b32 s1, 0
	s_waitcnt lgkmcnt(7)
	v_mfma_f32_32x32x16_bf16 v[34:49], v[244:247], v[200:203], v[34:49]
	v_add_u32_e32 v248, s60, v160
	v_lshl_add_u64 v[82:83], s[0:1], 0, v[186:187]
	v_lshl_add_u64 v[84:85], s[0:1], 0, v[188:189]
	v_mfma_f32_32x32x16_bf16 v[50:65], v[164:167], v[200:203], v[50:65]
	ds_read_b128 v[164:167], v248 offset:13312
	global_load_dwordx4 v[86:89], v[82:83], off
	global_load_dwordx4 v[90:93], v[84:85], off
	v_lshl_add_u64 v[82:83], s[8:9], 1, v[142:143]
	v_mfma_f32_32x32x16_bf16 v[34:49], v[168:171], v[204:207], v[34:49]
	ds_read_b128 v[168:171], v248 offset:17920
	global_load_dwordx4 v[82:85], v[82:83], off
	s_waitcnt lgkmcnt(6)
	v_mfma_f32_32x32x16_bf16 v[50:65], v[172:175], v[204:207], v[50:65]
	ds_read_b128 v[172:175], v248 offset:13344
	v_mfma_f32_32x32x16_bf16 v[34:49], v[176:179], v[208:211], v[34:49]
	ds_read_b128 v[176:179], v248 offset:17952
	v_mfma_f32_32x32x16_bf16 v[50:65], v[180:183], v[208:211], v[50:65]
	ds_read_b128 v[180:183], v248 offset:13376
	s_waitcnt lgkmcnt(6)
	v_mfma_f32_32x32x16_bf16 v[34:49], v[220:223], v[212:215], v[34:49]
	ds_read_b128 v[220:223], v248 offset:17984
	v_mfma_f32_32x32x16_bf16 v[50:65], v[224:227], v[212:215], v[50:65]
	ds_read_b128 v[224:227], v248 offset:13408
	v_mfma_f32_32x32x16_bf16 v[34:49], v[232:235], v[216:219], v[34:49]
	ds_read_b128 v[232:235], v248 offset:18016
	s_waitcnt lgkmcnt(8)
	v_mfma_f32_32x32x16_bf16 v[50:65], v[236:239], v[216:219], v[50:65]
	s_setprio 0
	s_waitcnt lgkmcnt(8)
	s_barrier
	v_max3_f32 v0, v34, v35, v36
	v_max3_f32 v106, v50, v51, v52
	v_max3_f32 v0, v0, v37, v38
	v_max3_f32 v106, v106, v53, v54
	v_max3_f32 v0, v0, v39, v40
	v_max3_f32 v106, v106, v55, v56
	v_max3_f32 v0, v0, v41, v42
	v_max3_f32 v106, v106, v57, v58
	v_max3_f32 v0, v0, v43, v44
	v_max3_f32 v106, v106, v59, v60
	v_max3_f32 v0, v0, v45, v46
	v_max3_f32 v106, v106, v61, v62
	v_max3_f32 v0, v0, v47, v48
	v_max3_f32 v106, v106, v63, v64
	v_max3_f32 v0, v0, v106, v49
	v_max_f32_e32 v0, v0, v65
	v_cmp_lt_f32_e32 vcc, s35, v0
	s_cbranch_vccnz .Lfm_b_resc
.Lfm_b_exp:
	v_exp_f32_e32 v34, v34
	v_exp_f32_e32 v50, v50
	v_exp_f32_e32 v35, v35
	v_exp_f32_e32 v51, v51
	v_exp_f32_e32 v42, v42
	v_exp_f32_e32 v58, v58
	v_exp_f32_e32 v43, v43
	v_exp_f32_e32 v59, v59
	v_exp_f32_e32 v36, v36
	v_exp_f32_e32 v52, v52
	v_exp_f32_e32 v37, v37
	v_exp_f32_e32 v53, v53
	v_exp_f32_e32 v44, v44
	v_exp_f32_e32 v60, v60
	v_exp_f32_e32 v45, v45
	v_exp_f32_e32 v61, v61
	v_exp_f32_e32 v38, v38
	v_exp_f32_e32 v54, v54
	v_exp_f32_e32 v39, v39
	v_exp_f32_e32 v55, v55
	v_exp_f32_e32 v46, v46
	v_exp_f32_e32 v62, v62
	v_exp_f32_e32 v47, v47
	v_exp_f32_e32 v63, v63
	v_exp_f32_e32 v40, v40
	v_exp_f32_e32 v56, v56
	v_exp_f32_e32 v41, v41
	v_exp_f32_e32 v57, v57
	v_exp_f32_e32 v48, v48
	v_exp_f32_e32 v64, v64
	v_exp_f32_e32 v49, v49
	v_exp_f32_e32 v65, v65
	v_pk_add_f32 v[106:107], v[34:35], v[50:51]
	v_pk_add_f32 v[108:109], v[36:37], v[52:53]
	v_pk_add_f32 v[110:111], v[38:39], v[54:55]
	v_pk_add_f32 v[112:113], v[40:41], v[56:57]
	v_pk_add_f32 v[114:115], v[42:43], v[58:59]
	v_pk_add_f32 v[116:117], v[44:45], v[60:61]
	v_pk_add_f32 v[118:119], v[46:47], v[62:63]
	v_pk_add_f32 v[120:121], v[48:49], v[64:65]
	v_pk_add_f32 v[106:107], v[106:107], v[108:109]
	v_pk_add_f32 v[110:111], v[110:111], v[112:113]
	v_pk_add_f32 v[114:115], v[114:115], v[116:117]
	v_pk_add_f32 v[118:119], v[118:119], v[120:121]
	v_pk_add_f32 v[106:107], v[106:107], v[110:111]
	v_pk_add_f32 v[114:115], v[114:115], v[118:119]
	v_pk_add_f32 v[106:107], v[106:107], v[114:115]
	v_add_f32_e32 v0, v106, v107
	v_cvt_pk_bf16_f32 v106, v34, v35
	v_cvt_pk_bf16_f32 v107, v36, v37
	v_cvt_pk_bf16_f32 v108, v38, v39
	v_cvt_pk_bf16_f32 v109, v40, v41
	v_cvt_pk_bf16_f32 v110, v42, v43
	v_cvt_pk_bf16_f32 v111, v44, v45
	v_cvt_pk_bf16_f32 v112, v46, v47
	v_cvt_pk_bf16_f32 v113, v48, v49
	v_cvt_pk_bf16_f32 v114, v50, v51
	v_cvt_pk_bf16_f32 v115, v52, v53
	v_cvt_pk_bf16_f32 v116, v54, v55
	v_cvt_pk_bf16_f32 v117, v56, v57
	v_cvt_pk_bf16_f32 v118, v58, v59
	v_cvt_pk_bf16_f32 v119, v60, v61
	v_cvt_pk_bf16_f32 v120, v62, v63
	v_cvt_pk_bf16_f32 v121, v64, v65
	v_add_f32_e32 v162, v162, v0
	s_waitcnt lgkmcnt(0)
	s_barrier
	v_mfma_f32_32x32x16_bf16 v[2:17], v[164:167], v[106:109], v[2:17]
	s_setprio 1
	v_add3_u32 v0, s58, v152, v153
	s_waitcnt vmcnt(3)
	ds_write_b128 v0, v[98:101]
	v_mfma_f32_32x32x16_bf16 v[18:33], v[168:171], v[106:109], v[18:33]
	v_add3_u32 v0, s58, v154, v155
	ds_write_b128 v0, v[94:97]
	v_mfma_f32_32x32x16_bf16 v[2:17], v[172:175], v[110:113], v[2:17]
	v_add3_u32 v0, s58, v156, v140
	ds_write_b128 v0, v[102:105] offset:13312
	v_add_u32_e32 v249, s57, v157
	v_mfma_f32_32x32x16_bf16 v[18:33], v[176:179], v[110:113], v[18:33]
	ds_read_b128 v[236:239], v249
	ds_read_b128 v[240:243], v249 offset:6656
	ds_read_b128 v[244:247], v249 offset:32
	v_mfma_f32_32x32x16_bf16 v[2:17], v[180:183], v[114:117], v[2:17]
	ds_read_b128 v[164:167], v249 offset:6688
	ds_read_b128 v[168:171], v249 offset:64
	ds_read_b128 v[172:175], v249 offset:6720
	v_mfma_f32_32x32x16_bf16 v[18:33], v[220:223], v[114:117], v[18:33]
	ds_read_b128 v[176:179], v249 offset:96
	ds_read_b128 v[180:183], v249 offset:6752
	ds_read_b128 v[220:223], v249 offset:128
	v_mfma_f32_32x32x16_bf16 v[2:17], v[224:227], v[118:121], v[2:17]
	ds_read_b128 v[224:227], v249 offset:6784
	s_add_i32 s59, s59, 2
	s_mov_b32 s0, s58
	v_mfma_f32_32x32x16_bf16 v[18:33], v[232:235], v[118:121], v[18:33]
	ds_read_b128 v[232:235], v249 offset:160
	s_mov_b32 s58, s57
	s_mov_b32 s57, s60
	s_mov_b32 s60, s0
	s_addk_i32 s54, 0x80
	s_waitcnt lgkmcnt(9)
	v_mfma_f32_32x32x16_bf16 v[34:49], v[236:239], v[196:199], v[66:81]
	ds_read_b128 v[236:239], v249 offset:6816
	s_add_i32 s1, s59, 3
	s_lshl_b32 s8, s1, 6
	v_mfma_f32_32x32x16_bf16 v[50:65], v[240:243], v[196:199], v[66:81]
	s_mul_i32 s20, s8, 0x600
	s_mov_b32 s21, 0
	s_waitcnt lgkmcnt(7)
	v_mfma_f32_32x32x16_bf16 v[34:49], v[244:247], v[200:203], v[34:49]
	v_add_u32_e32 v248, s58, v160
	v_lshl_add_u64 v[94:95], s[20:21], 0, v[186:187]
	v_lshl_add_u64 v[96:97], s[20:21], 0, v[188:189]
	v_mfma_f32_32x32x16_bf16 v[50:65], v[164:167], v[200:203], v[50:65]
	ds_read_b128 v[164:167], v248 offset:13312
	v_lshl_add_u64 v[102:103], s[8:9], 1, v[142:143]
	global_load_dwordx4 v[98:101], v[94:95], off
	s_nop 0
	v_mfma_f32_32x32x16_bf16 v[34:49], v[168:171], v[204:207], v[34:49]
	ds_read_b128 v[168:171], v248 offset:17920
	global_load_dwordx4 v[94:97], v[96:97], off
	global_load_dwordx4 v[102:105], v[102:103], off
	s_waitcnt lgkmcnt(6)
	v_mfma_f32_32x32x16_bf16 v[50:65], v[172:175], v[204:207], v[50:65]
	ds_read_b128 v[172:175], v248 offset:13344
	v_mfma_f32_32x32x16_bf16 v[34:49], v[176:179], v[208:211], v[34:49]
	ds_read_b128 v[176:179], v248 offset:17952
	v_mfma_f32_32x32x16_bf16 v[50:65], v[180:183], v[208:211], v[50:65]
	ds_read_b128 v[180:183], v248 offset:13376
	s_waitcnt lgkmcnt(6)
	v_mfma_f32_32x32x16_bf16 v[34:49], v[220:223], v[212:215], v[34:49]
	ds_read_b128 v[220:223], v248 offset:17984
	v_mfma_f32_32x32x16_bf16 v[50:65], v[224:227], v[212:215], v[50:65]
	ds_read_b128 v[224:227], v248 offset:13408
	v_mfma_f32_32x32x16_bf16 v[34:49], v[232:235], v[216:219], v[34:49]
	ds_read_b128 v[232:235], v248 offset:18016
	s_waitcnt lgkmcnt(8)
	v_mfma_f32_32x32x16_bf16 v[50:65], v[236:239], v[216:219], v[50:65]
	s_setprio 0
	s_add_i32 s4, s55, s59
	s_cmp_lt_i32 s4, -1
	s_waitcnt lgkmcnt(8)
	s_barrier
	s_cbranch_scc1 .Lfm_head
	s_mov_b32 s0, s58
	s_mov_b32 s58, s60
	s_branch .LBB0_1037

; #define ATT_BAR() do { asm volatile("s_waitcnt lgkmcnt(0)" ::: "memory"); __builtin_amdgcn_s_barrier(); asm volatile("" ::: "memory"); } while (0)
; template <int DK, int DV>
; __device__ __forceinline__ void attn_unit(LAS unsigned char* lds, const bf16* Qp, int ldq, const bf16* Kp, int ldk, const bf16* VTp, bf16* Op, int ldo, int qb) {
;     ...
;     ATT_LOAD(0, kra, vra); ATT_LOAD(1, krb, vrb);
;     ATT_STORE(0, kra, vra); ATT_STORE(BUF, krb, vrb);
;     ATT_LOAD(2, krb, vrb);
;     __syncthreads();
;     float mrun = 0.f, lrun = 0.f;
;     f32x16 o[NDB];
; #pragma unroll
;     for (int db = 0; db < NDB; ++db)
; #pragma unroll
;         for (int r = 0; r < 16; ++r) o[db][r] = 0.f;
;     f32x16 s0, s1;
;     const f32x16 zacc = {0.f, 0.f, 0.f, 0.f, 0.f, 0.f, 0.f, 0.f, 0.f, 0.f, 0.f, 0.f, 0.f, 0.f, 0.f, 0.f};
;     f32x16 negm = zacc;
;     constexpr float ATT_THR = 8.f;
;     ATT_QK(0, zacc);
;     if (grpB) ATT_BAR();
;     int bcur = 0, bnext = BUF, bfree = 2 * BUF;
; #pragma unroll 1
;     for (int t = 0; t < NT; t += 2) {
.LBB0_1071:
	ds_read_b128 v[232:235], v189
	ds_read_b128 v[236:239], v189 offset:1024
	ds_read_b128 v[240:243], v189 offset:2048
	ds_read_b128 v[244:247], v189 offset:3072
	v_mov_b32_e32 v14, v1
	v_mov_b32_e32 v15, v1
	s_lshl_b32 s43, s1, 2
	v_lshl_add_u64 v[182:183], v[2:3], 1, s[4:5]
	v_or_b32_e32 v192, s35, v4
	v_lshlrev_b32_e32 v191, 2, v5
	v_mov_b32_e32 v0, v1
	v_mov_b32_e32 v2, v1
	v_mov_b32_e32 v3, v1
	v_mov_b32_e32 v4, v1
	v_mov_b32_e32 v5, v1
	v_mov_b32_e32 v6, v1
	v_mov_b32_e32 v7, v1
	v_mov_b32_e32 v8, v1
	v_mov_b32_e32 v9, v1
	v_mov_b32_e32 v10, v1
	v_mov_b32_e32 v11, v1
	v_mov_b32_e32 v12, v1
	v_mov_b32_e32 v13, v1
	v_mov_b64_e32 v[30:31], v[14:15]
	v_mov_b64_e32 v[46:47], v[14:15]
	v_mov_b64_e32 v[62:63], v[14:15]
	v_mov_b64_e32 v[78:79], v[14:15]
	v_mov_b64_e32 v[126:127], v[14:15]
	s_lshl_b32 s42, s0, 13
	s_add_i32 s44, s43, 4
	s_or_b32 s45, s43, 3
	s_or_b32 s46, s35, 31
	s_mov_b32 s47, 0
	s_sub_i32 s48, 0, s43
	s_sub_i32 s49, 0, s8
	v_subrev_u32_e32 v194, s8, v191
	s_mov_b32 s50, 0xd800
	s_movk_i32 s51, 0x6c00
	v_mov_b32_e32 v193, 0
	v_mov_b64_e32 v[28:29], v[12:13]
	v_mov_b64_e32 v[26:27], v[10:11]
	v_mov_b64_e32 v[24:25], v[8:9]
	v_mov_b64_e32 v[22:23], v[6:7]
	v_mov_b64_e32 v[20:21], v[4:5]
	v_mov_b64_e32 v[18:19], v[2:3]
	v_mov_b64_e32 v[16:17], v[0:1]
	v_mov_b64_e32 v[44:45], v[12:13]
	v_mov_b64_e32 v[42:43], v[10:11]
	v_mov_b64_e32 v[40:41], v[8:9]
	v_mov_b64_e32 v[38:39], v[6:7]
	v_mov_b64_e32 v[36:37], v[4:5]
	v_mov_b64_e32 v[34:35], v[2:3]
	v_mov_b64_e32 v[32:33], v[0:1]
	v_mov_b64_e32 v[60:61], v[12:13]
	v_mov_b64_e32 v[58:59], v[10:11]
	v_mov_b64_e32 v[56:57], v[8:9]
	v_mov_b64_e32 v[54:55], v[6:7]
	v_mov_b64_e32 v[52:53], v[4:5]
	v_mov_b64_e32 v[50:51], v[2:3]
	v_mov_b64_e32 v[48:49], v[0:1]
	v_mov_b64_e32 v[76:77], v[12:13]
	v_mov_b64_e32 v[74:75], v[10:11]
	v_mov_b64_e32 v[72:73], v[8:9]
	v_mov_b64_e32 v[70:71], v[6:7]
	v_mov_b64_e32 v[68:69], v[4:5]
	v_mov_b64_e32 v[66:67], v[2:3]
	v_mov_b64_e32 v[64:65], v[0:1]
	v_mov_b32_e32 v195, 0
	v_mov_b64_e32 v[124:125], v[12:13]
	v_mov_b64_e32 v[122:123], v[10:11]
	v_mov_b64_e32 v[120:121], v[8:9]
	v_mov_b64_e32 v[118:119], v[6:7]
	v_mov_b64_e32 v[116:117], v[4:5]
	v_mov_b64_e32 v[114:115], v[2:3]
	v_mov_b64_e32 v[112:113], v[0:1]
	s_mov_b32 s0, 0
	s_mov_b32 s54, 0
	s_add_i32 s1, s54, 3
	s_cmp_lt_u32 s1, s44
	s_cselect_b32 s1, s1, s45
	s_lshl_b32 s8, s1, 6
	v_add_u32_e32 v2, s8, v174
	v_ashrrev_i32_e32 v3, 31, v2
	v_lshlrev_b64 v[2:3], 10, v[2:3]
	v_lshl_add_u64 v[6:7], s[8:9], 1, v[176:177]
	v_lshl_add_u64 v[2:3], v[182:183], 0, v[2:3]
	v_lshl_add_u64 v[4:5], v[6:7], 0, v[178:179]
	v_lshl_add_u64 v[6:7], v[6:7], 0, v[180:181]
	global_load_dwordx4 v[10:13], v[2:3], off
	s_nop 0
	global_load_dwordx4 v[2:5], v[4:5], off
	global_load_dwordx4 v[6:9], v[6:7], off
	s_add_i32 s4, s48, s54
	s_cmp_lt_i32 s4, -1
	s_cbranch_scc1 .Lfd_entry

.Lfd_head:
	v_max3_f32 v0, v80, v81, v82
	v_max3_f32 v14, v96, v97, v98
	v_max3_f32 v0, v0, v83, v84
	v_max3_f32 v14, v14, v99, v100
	v_max3_f32 v0, v0, v85, v86
	v_max3_f32 v14, v14, v101, v102
	v_max3_f32 v0, v0, v87, v88
	v_max3_f32 v14, v14, v103, v104
	v_max3_f32 v0, v0, v89, v90
	v_max3_f32 v14, v14, v105, v106
	v_max3_f32 v0, v0, v91, v92
	v_max3_f32 v14, v14, v107, v108
	v_max3_f32 v0, v0, v93, v94
	v_max3_f32 v14, v14, v109, v110
	v_max3_f32 v0, v0, v14, v95
	v_max_f32_e32 v0, v0, v111
	s_cmp_lg_u32 s47, 0
	s_cselect_b64 s[18:19], -1, 0
	s_cmp_eq_u32 s47, 0
	s_cbranch_scc1 .Lfd_a_xchg
	v_cmp_lt_f32_e32 vcc, s33, v0
	s_cbranch_vccnz .Lfd_a_xchg
.Lfd_a_exp:
	v_exp_f32_e32 v80, v80
	v_exp_f32_e32 v96, v96
	v_exp_f32_e32 v81, v81
	v_exp_f32_e32 v97, v97
	v_exp_f32_e32 v88, v88
	v_exp_f32_e32 v104, v104
	v_exp_f32_e32 v89, v89
	v_exp_f32_e32 v105, v105
	v_exp_f32_e32 v82, v82
	v_exp_f32_e32 v98, v98
	v_exp_f32_e32 v83, v83
	v_exp_f32_e32 v99, v99
	v_exp_f32_e32 v90, v90
	v_exp_f32_e32 v106, v106
	v_exp_f32_e32 v91, v91
	v_exp_f32_e32 v107, v107
	v_exp_f32_e32 v84, v84
	v_exp_f32_e32 v100, v100
	v_exp_f32_e32 v85, v85
	v_exp_f32_e32 v101, v101
	v_exp_f32_e32 v92, v92
	v_exp_f32_e32 v108, v108
	v_exp_f32_e32 v93, v93
	v_exp_f32_e32 v109, v109
	v_exp_f32_e32 v86, v86
	v_exp_f32_e32 v102, v102
	v_exp_f32_e32 v87, v87
	v_exp_f32_e32 v103, v103
	v_exp_f32_e32 v94, v94
	v_exp_f32_e32 v110, v110
	v_exp_f32_e32 v95, v95
	v_exp_f32_e32 v111, v111
	v_pk_add_f32 v[156:157], v[80:81], v[96:97]
	v_pk_add_f32 v[158:159], v[82:83], v[98:99]
	v_pk_add_f32 v[160:161], v[84:85], v[100:101]
	v_pk_add_f32 v[162:163], v[86:87], v[102:103]
	v_pk_add_f32 v[164:165], v[88:89], v[104:105]
	v_pk_add_f32 v[166:167], v[90:91], v[106:107]
	v_pk_add_f32 v[168:169], v[92:93], v[108:109]
	v_pk_add_f32 v[170:171], v[94:95], v[110:111]
	v_pk_add_f32 v[156:157], v[156:157], v[158:159]
	v_pk_add_f32 v[160:161], v[160:161], v[162:163]
	v_pk_add_f32 v[164:165], v[164:165], v[166:167]
	v_pk_add_f32 v[168:169], v[168:169], v[170:171]
	v_pk_add_f32 v[156:157], v[156:157], v[160:161]
	v_pk_add_f32 v[164:165], v[164:165], v[168:169]
	v_pk_add_f32 v[156:157], v[156:157], v[164:165]
	v_add_f32_e32 v0, v156, v157
	v_cvt_pk_bf16_f32 v156, v80, v81
	v_cvt_pk_bf16_f32 v157, v82, v83
	v_cvt_pk_bf16_f32 v158, v84, v85
	v_cvt_pk_bf16_f32 v159, v86, v87
	v_cvt_pk_bf16_f32 v160, v88, v89
	v_cvt_pk_bf16_f32 v161, v90, v91
	v_cvt_pk_bf16_f32 v162, v92, v93
	v_cvt_pk_bf16_f32 v163, v94, v95
	v_cvt_pk_bf16_f32 v164, v96, v97
	v_cvt_pk_bf16_f32 v165, v98, v99
	v_cvt_pk_bf16_f32 v166, v100, v101
	v_cvt_pk_bf16_f32 v167, v102, v103
	v_cvt_pk_bf16_f32 v168, v104, v105
	v_cvt_pk_bf16_f32 v169, v106, v107
	v_cvt_pk_bf16_f32 v170, v108, v109
	v_cvt_pk_bf16_f32 v171, v110, v111
	v_add_f32_e32 v193, v193, v0
	s_waitcnt lgkmcnt(0)
	s_barrier
	v_mfma_f32_32x32x16_bf16 v[64:79], v[196:199], v[156:159], v[64:79]
	s_setprio 1
	v_add_u32_e32 v14, s50, v188
	s_waitcnt vmcnt(3)
	ds_write_b128 v14, v[136:139]
	v_mfma_f32_32x32x16_bf16 v[48:63], v[200:203], v[156:159], v[48:63]
	ds_read_b128 v[196:199], v248 offset:9280
	v_add_u32_e32 v14, s50, v186
	v_add_u32_e32 v15, v14, v175
	v_mfma_f32_32x32x16_bf16 v[32:47], v[204:207], v[156:159], v[32:47]
	ds_read_b128 v[200:203], v248 offset:13888
	v_add_u32_e32 v14, v14, v187
	ds_write_b128 v15, v[128:131] offset:9216
	v_mfma_f32_32x32x16_bf16 v[16:31], v[208:211], v[156:159], v[16:31]
	ds_read_b128 v[204:207], v248 offset:18496
	ds_write_b128 v14, v[132:135] offset:9216
	v_mfma_f32_32x32x16_bf16 v[64:79], v[212:215], v[160:163], v[64:79]
	ds_read_b128 v[208:211], v248 offset:23104
	v_add_u32_e32 v249, s55, v190
	v_mfma_f32_32x32x16_bf16 v[48:63], v[216:219], v[160:163], v[48:63]
	ds_read_b128 v[212:215], v248 offset:9312
	v_mfma_f32_32x32x16_bf16 v[32:47], v[220:223], v[160:163], v[32:47]
	ds_read_b128 v[216:219], v248 offset:13920
	v_mfma_f32_32x32x16_bf16 v[16:31], v[224:227], v[160:163], v[16:31]
	ds_read_b128 v[220:223], v248 offset:18528
	ds_read_b128 v[224:227], v248 offset:23136
	s_waitcnt lgkmcnt(4)
	v_mfma_f32_32x32x16_bf16 v[64:79], v[196:199], v[164:167], v[64:79]
	ds_read_b128 v[196:199], v249
	s_add_i32 s0, s54, 4
	s_lshl_b32 s8, s0, 6
	v_mfma_f32_32x32x16_bf16 v[48:63], v[200:203], v[164:167], v[48:63]
	ds_read_b128 v[200:203], v249 offset:4608
	v_add_u32_e32 v14, s8, v174
	v_ashrrev_i32_e32 v15, 31, v14
	v_mfma_f32_32x32x16_bf16 v[32:47], v[204:207], v[164:167], v[32:47]
	ds_read_b128 v[204:207], v249 offset:32
	v_lshlrev_b64 v[14:15], 10, v[14:15]
	v_lshl_add_u64 v[132:133], s[8:9], 1, v[176:177]
	v_mfma_f32_32x32x16_bf16 v[16:31], v[208:211], v[164:167], v[16:31]
	ds_read_b128 v[208:211], v249 offset:4640
	v_lshl_add_u64 v[14:15], v[182:183], 0, v[14:15]
	v_lshl_add_u64 v[128:129], v[132:133], 0, v[178:179]
	s_waitcnt lgkmcnt(4)
	v_mfma_f32_32x32x16_bf16 v[64:79], v[212:215], v[168:171], v[64:79]
	ds_read_b128 v[212:215], v249 offset:64
	global_load_dwordx4 v[136:139], v[14:15], off
	s_nop 0
	v_mfma_f32_32x32x16_bf16 v[48:63], v[216:219], v[168:171], v[48:63]
	ds_read_b128 v[216:219], v249 offset:4672
	global_load_dwordx4 v[128:131], v[128:129], off
	v_lshl_add_u64 v[14:15], v[132:133], 0, v[180:181]
	v_mfma_f32_32x32x16_bf16 v[32:47], v[220:223], v[168:171], v[32:47]
	ds_read_b128 v[220:223], v249 offset:96
	global_load_dwordx4 v[132:135], v[14:15], off
	v_mfma_f32_32x32x16_bf16 v[16:31], v[224:227], v[168:171], v[16:31]
	ds_read_b128 v[224:227], v249 offset:4704
	v_add_u32_e32 v248, s55, v190
	s_waitcnt lgkmcnt(4)
	v_mfma_f32_32x32x16_bf16 v[80:95], v[196:199], v[232:235], v[112:127]
	ds_read_b128 v[196:199], v248 offset:9216
	v_mfma_f32_32x32x16_bf16 v[96:111], v[200:203], v[232:235], v[112:127]
	ds_read_b128 v[200:203], v248 offset:13824
	v_mfma_f32_32x32x16_bf16 v[80:95], v[204:207], v[236:239], v[80:95]
	ds_read_b128 v[204:207], v248 offset:18432
	v_mfma_f32_32x32x16_bf16 v[96:111], v[208:211], v[236:239], v[96:111]
	ds_read_b128 v[208:211], v248 offset:23040
	s_waitcnt lgkmcnt(4)
	v_mfma_f32_32x32x16_bf16 v[80:95], v[212:215], v[240:243], v[80:95]
	ds_read_b128 v[212:215], v248 offset:9248
	v_mfma_f32_32x32x16_bf16 v[96:111], v[216:219], v[240:243], v[96:111]
	ds_read_b128 v[216:219], v248 offset:13856
	v_mfma_f32_32x32x16_bf16 v[80:95], v[220:223], v[244:247], v[80:95]
	ds_read_b128 v[220:223], v248 offset:18464
	v_mfma_f32_32x32x16_bf16 v[96:111], v[224:227], v[244:247], v[96:111]
	ds_read_b128 v[224:227], v248 offset:23072
	s_setprio 0
	s_waitcnt lgkmcnt(8)
	s_barrier
	v_max3_f32 v14, v80, v81, v82
	v_max3_f32 v15, v96, v97, v98
	v_max3_f32 v14, v14, v83, v84
	v_max3_f32 v15, v15, v99, v100
	v_max3_f32 v14, v14, v85, v86
	v_max3_f32 v15, v15, v101, v102
	v_max3_f32 v14, v14, v87, v88
	v_max3_f32 v15, v15, v103, v104
	v_max3_f32 v14, v14, v89, v90
	v_max3_f32 v15, v15, v105, v106
	v_max3_f32 v14, v14, v91, v92
	v_max3_f32 v15, v15, v107, v108
	v_max3_f32 v14, v14, v93, v94
	v_max3_f32 v15, v15, v109, v110
	v_max3_f32 v14, v14, v15, v95
	v_max_f32_e32 v14, v14, v111
	v_cmp_lt_f32_e32 vcc, s33, v14
	s_cbranch_vccnz .Lfd_b_resc
.Lfd_b_exp:
	v_exp_f32_e32 v80, v80
	v_exp_f32_e32 v96, v96
	v_exp_f32_e32 v81, v81
	v_exp_f32_e32 v97, v97
	v_exp_f32_e32 v88, v88
	v_exp_f32_e32 v104, v104
	v_exp_f32_e32 v89, v89
	v_exp_f32_e32 v105, v105
	v_exp_f32_e32 v82, v82
	v_exp_f32_e32 v98, v98
	v_exp_f32_e32 v83, v83
	v_exp_f32_e32 v99, v99
	v_exp_f32_e32 v90, v90
	v_exp_f32_e32 v106, v106
	v_exp_f32_e32 v91, v91
	v_exp_f32_e32 v107, v107
	v_exp_f32_e32 v84, v84
	v_exp_f32_e32 v100, v100
	v_exp_f32_e32 v85, v85
	v_exp_f32_e32 v101, v101
	v_exp_f32_e32 v92, v92
	v_exp_f32_e32 v108, v108
	v_exp_f32_e32 v93, v93
	v_exp_f32_e32 v109, v109
	v_exp_f32_e32 v86, v86
	v_exp_f32_e32 v102, v102
	v_exp_f32_e32 v87, v87
	v_exp_f32_e32 v103, v103
	v_exp_f32_e32 v94, v94
	v_exp_f32_e32 v110, v110
	v_exp_f32_e32 v95, v95
	v_exp_f32_e32 v111, v111
	v_pk_add_f32 v[140:141], v[80:81], v[96:97]
	v_pk_add_f32 v[142:143], v[82:83], v[98:99]
	v_pk_add_f32 v[144:145], v[84:85], v[100:101]
	v_pk_add_f32 v[146:147], v[86:87], v[102:103]
	v_pk_add_f32 v[148:149], v[88:89], v[104:105]
	v_pk_add_f32 v[150:151], v[90:91], v[106:107]
	v_pk_add_f32 v[152:153], v[92:93], v[108:109]
	v_pk_add_f32 v[154:155], v[94:95], v[110:111]
	v_pk_add_f32 v[140:141], v[140:141], v[142:143]
	v_pk_add_f32 v[144:145], v[144:145], v[146:147]
	v_pk_add_f32 v[148:149], v[148:149], v[150:151]
	v_pk_add_f32 v[152:153], v[152:153], v[154:155]
	v_pk_add_f32 v[140:141], v[140:141], v[144:145]
	v_pk_add_f32 v[148:149], v[148:149], v[152:153]
	v_pk_add_f32 v[140:141], v[140:141], v[148:149]
	v_add_f32_e32 v14, v140, v141
	v_cvt_pk_bf16_f32 v140, v80, v81
	v_cvt_pk_bf16_f32 v141, v82, v83
	v_cvt_pk_bf16_f32 v142, v84, v85
	v_cvt_pk_bf16_f32 v143, v86, v87
	v_cvt_pk_bf16_f32 v144, v88, v89
	v_cvt_pk_bf16_f32 v145, v90, v91
	v_cvt_pk_bf16_f32 v146, v92, v93
	v_cvt_pk_bf16_f32 v147, v94, v95
	v_cvt_pk_bf16_f32 v148, v96, v97
	v_cvt_pk_bf16_f32 v149, v98, v99
	v_cvt_pk_bf16_f32 v150, v100, v101
	v_cvt_pk_bf16_f32 v151, v102, v103
	v_cvt_pk_bf16_f32 v152, v104, v105
	v_cvt_pk_bf16_f32 v153, v106, v107
	v_cvt_pk_bf16_f32 v154, v108, v109
	v_cvt_pk_bf16_f32 v155, v110, v111
	v_add_f32_e32 v193, v193, v14
	s_waitcnt lgkmcnt(0)
	s_barrier
	v_mfma_f32_32x32x16_bf16 v[64:79], v[196:199], v[140:143], v[64:79]
	s_setprio 1
	v_add_u32_e32 v0, s51, v188
	s_waitcnt vmcnt(3)
	ds_write_b128 v0, v[10:13]
	v_mfma_f32_32x32x16_bf16 v[48:63], v[200:203], v[140:143], v[48:63]
	ds_read_b128 v[196:199], v248 offset:9280
	v_add_u32_e32 v0, s51, v186
	v_add_u32_e32 v10, v0, v175
	v_mfma_f32_32x32x16_bf16 v[32:47], v[204:207], v[140:143], v[32:47]
	ds_read_b128 v[200:203], v248 offset:13888
	v_add_u32_e32 v0, v0, v187
	ds_write_b128 v10, v[2:5] offset:9216
	v_mfma_f32_32x32x16_bf16 v[16:31], v[208:211], v[140:143], v[16:31]
	ds_read_b128 v[204:207], v248 offset:18496
	ds_write_b128 v0, v[6:9] offset:9216
	v_mfma_f32_32x32x16_bf16 v[64:79], v[212:215], v[144:147], v[64:79]
	ds_read_b128 v[208:211], v248 offset:23104
	v_add_u32_e32 v249, s50, v190
	v_mfma_f32_32x32x16_bf16 v[48:63], v[216:219], v[144:147], v[48:63]
	ds_read_b128 v[212:215], v248 offset:9312
	s_add_i32 s54, s54, 2
	s_mov_b32 s0, s51
	v_mfma_f32_32x32x16_bf16 v[32:47], v[220:223], v[144:147], v[32:47]
	ds_read_b128 v[216:219], v248 offset:13920
	s_mov_b32 s51, s50
	s_mov_b32 s50, s55
	v_mfma_f32_32x32x16_bf16 v[16:31], v[224:227], v[144:147], v[16:31]
	ds_read_b128 v[220:223], v248 offset:18528
	ds_read_b128 v[224:227], v248 offset:23136
	s_mov_b32 s55, s0
	s_addk_i32 s47, 0x80
	s_waitcnt lgkmcnt(4)
	v_mfma_f32_32x32x16_bf16 v[64:79], v[196:199], v[148:151], v[64:79]
	ds_read_b128 v[196:199], v249
	s_add_i32 s1, s54, 3
	s_lshl_b32 s8, s1, 6
	v_mfma_f32_32x32x16_bf16 v[48:63], v[200:203], v[148:151], v[48:63]
	ds_read_b128 v[200:203], v249 offset:4608
	v_add_u32_e32 v2, s8, v174
	v_ashrrev_i32_e32 v3, 31, v2
	v_mfma_f32_32x32x16_bf16 v[32:47], v[204:207], v[148:151], v[32:47]
	ds_read_b128 v[204:207], v249 offset:32
	v_lshlrev_b64 v[2:3], 10, v[2:3]
	v_lshl_add_u64 v[6:7], s[8:9], 1, v[176:177]
	v_mfma_f32_32x32x16_bf16 v[16:31], v[208:211], v[148:151], v[16:31]
	ds_read_b128 v[208:211], v249 offset:4640
	v_lshl_add_u64 v[2:3], v[182:183], 0, v[2:3]
	v_lshl_add_u64 v[4:5], v[6:7], 0, v[178:179]
	s_waitcnt lgkmcnt(4)
	v_mfma_f32_32x32x16_bf16 v[64:79], v[212:215], v[152:155], v[64:79]
	ds_read_b128 v[212:215], v249 offset:64
	v_lshl_add_u64 v[6:7], v[6:7], 0, v[180:181]
	global_load_dwordx4 v[10:13], v[2:3], off
	v_mfma_f32_32x32x16_bf16 v[48:63], v[216:219], v[152:155], v[48:63]
	ds_read_b128 v[216:219], v249 offset:4672
	s_nop 0
	global_load_dwordx4 v[2:5], v[4:5], off
	v_mfma_f32_32x32x16_bf16 v[32:47], v[220:223], v[152:155], v[32:47]
	ds_read_b128 v[220:223], v249 offset:96
	global_load_dwordx4 v[6:9], v[6:7], off
	v_mfma_f32_32x32x16_bf16 v[16:31], v[224:227], v[152:155], v[16:31]
	ds_read_b128 v[224:227], v249 offset:4704
	v_add_u32_e32 v248, s51, v190
	s_waitcnt lgkmcnt(4)
	v_mfma_f32_32x32x16_bf16 v[80:95], v[196:199], v[232:235], v[112:127]
	ds_read_b128 v[196:199], v248 offset:9216
	v_mfma_f32_32x32x16_bf16 v[96:111], v[200:203], v[232:235], v[112:127]
	ds_read_b128 v[200:203], v248 offset:13824
	v_mfma_f32_32x32x16_bf16 v[80:95], v[204:207], v[236:239], v[80:95]
	ds_read_b128 v[204:207], v248 offset:18432
	v_mfma_f32_32x32x16_bf16 v[96:111], v[208:211], v[236:239], v[96:111]
	ds_read_b128 v[208:211], v248 offset:23040
	s_waitcnt lgkmcnt(4)
	v_mfma_f32_32x32x16_bf16 v[80:95], v[212:215], v[240:243], v[80:95]
	ds_read_b128 v[212:215], v248 offset:9248
	v_mfma_f32_32x32x16_bf16 v[96:111], v[216:219], v[240:243], v[96:111]
	ds_read_b128 v[216:219], v248 offset:13856
	s_add_i32 s4, s48, s54
	v_mfma_f32_32x32x16_bf16 v[80:95], v[220:223], v[244:247], v[80:95]
	ds_read_b128 v[220:223], v248 offset:18464
	v_mfma_f32_32x32x16_bf16 v[96:111], v[224:227], v[244:247], v[96:111]
	ds_read_b128 v[224:227], v248 offset:23072
	s_cmp_lt_i32 s4, -1
	s_setprio 0
	s_waitcnt lgkmcnt(8)
	s_barrier
	s_cbranch_scc1 .Lfd_head
	s_mov_b32 s0, s51
	s_mov_b32 s51, s55
	s_branch .LBB0_1072
